# P1 sample-row reduction chain uses v_mov_b32_dpp / permlane swaps instead of ds_bpermute (on top of tail DPP version)
# speedup vs baseline: 1.0077x; 1.0077x over previous
.LBB0_156:
	v_mov_b64_e32 v[0:1], s[78:79]
	v_mad_i64_i32 v[84:85], s[52:53], v40, s33, v[0:1]
	v_lshl_add_u64 v[94:95], v[84:85], 0, s[8:9]
	v_lshl_add_u64 v[96:97], v[84:85], 0, s[12:13]
	v_lshl_add_u64 v[8:9], v[94:95], 0, v[44:45]
	v_lshl_add_u64 v[12:13], v[96:97], 0, v[44:45]
	v_lshl_add_u64 v[98:99], v[84:85], 0, s[14:15]
	v_lshl_add_u64 v[100:101], v[84:85], 0, s[16:17]
	global_load_dwordx4 v[0:3], v[46:47], off
	global_load_dwordx4 v[4:7], v[48:49], off
	s_nop 0
	global_load_dwordx4 v[8:11], v[8:9], off
	s_nop 0
	global_load_dwordx4 v[12:15], v[12:13], off
	v_lshl_add_u64 v[16:17], v[98:99], 0, v[44:45]
	v_lshl_add_u64 v[20:21], v[100:101], 0, v[44:45]
	v_lshl_add_u64 v[102:103], v[84:85], 0, s[18:19]
	v_lshl_add_u64 v[64:65], v[84:85], 0, s[20:21]
	v_lshl_add_u64 v[66:67], v[84:85], 0, s[24:25]
	global_load_dwordx4 v[16:19], v[16:17], off
	s_nop 0
	global_load_dwordx4 v[20:23], v[20:21], off
	v_lshl_add_u64 v[24:25], v[102:103], 0, v[44:45]
	v_lshl_add_u64 v[28:29], v[64:65], 0, v[44:45]
	v_lshl_add_u64 v[32:33], v[66:67], 0, v[44:45]
	v_lshl_add_u64 v[70:71], v[84:85], 0, s[28:29]
	global_load_dwordx4 v[24:27], v[24:25], off
	s_nop 0
	global_load_dwordx4 v[28:31], v[28:29], off
	v_lshl_add_u64 v[72:73], v[70:71], 0, v[44:45]
	global_load_dwordx4 v[32:35], v[32:33], off
	v_lshl_add_u64 v[68:69], v[84:85], 0, s[26:27]
	global_load_dwordx4 v[86:89], v[72:73], off
	v_lshl_add_u64 v[72:73], v[84:85], 0, s[30:31]
	v_lshl_add_u64 v[74:75], v[72:73], 0, v[44:45]
	v_lshl_add_u64 v[36:37], v[68:69], 0, v[44:45]
	global_load_dwordx4 v[90:93], v[74:75], off
	v_lshl_add_u64 v[74:75], v[84:85], 0, s[34:35]
	v_lshl_add_u64 v[76:77], v[84:85], 0, s[36:37]
	global_load_dwordx4 v[36:39], v[36:37], off
	v_lshl_add_u64 v[78:79], v[74:75], 0, v[44:45]
	v_lshl_add_u64 v[80:81], v[76:77], 0, v[44:45]
	global_load_dwordx4 v[106:109], v[78:79], off
	global_load_dwordx4 v[110:113], v[80:81], off
	v_lshl_add_u64 v[78:79], v[84:85], 0, s[38:39]
	v_lshl_add_u64 v[80:81], v[84:85], 0, s[40:41]
	v_lshl_add_u64 v[82:83], v[78:79], 0, v[44:45]
	v_lshl_add_u64 v[118:119], v[80:81], 0, v[44:45]
	global_load_dwordx4 v[114:117], v[82:83], off
	s_nop 0
	global_load_dwordx4 v[118:121], v[118:119], off
	v_lshl_add_u64 v[82:83], v[84:85], 0, s[42:43]
	v_lshl_add_u64 v[84:85], v[84:85], 0, s[44:45]
	v_lshl_add_u64 v[122:123], v[82:83], 0, v[44:45]
	v_lshl_add_u64 v[126:127], v[84:85], 0, v[44:45]
	global_load_dwordx4 v[122:125], v[122:123], off
	s_nop 0
	global_load_dwordx4 v[126:129], v[126:127], off
	s_nop 0
	global_load_dwordx4 v[130:133], v[50:51], off
	global_load_dwordx4 v[134:137], v[46:47], off offset:1024
	v_lshl_add_u64 v[138:139], v[94:95], 0, v[146:147]
	v_lshl_add_u64 v[142:143], v[96:97], 0, v[146:147]
	global_load_dwordx4 v[138:141], v[138:139], off
	s_nop 0
	global_load_dwordx4 v[148:151], v[52:53], off
	global_load_dwordx4 v[152:155], v[142:143], off
	v_lshl_add_u64 v[142:143], v[98:99], 0, v[146:147]
	global_load_dwordx4 v[156:159], v[142:143], off
	v_lshl_add_u64 v[142:143], v[100:101], 0, v[146:147]
	global_load_dwordx4 v[160:163], v[142:143], off
	v_lshl_add_u64 v[142:143], v[102:103], 0, v[146:147]
	v_lshl_add_u64 v[168:169], v[64:65], 0, v[146:147]
	v_lshl_add_u64 v[172:173], v[66:67], 0, v[146:147]
	v_lshl_add_u64 v[176:177], v[68:69], 0, v[146:147]
	v_lshl_add_u64 v[180:181], v[70:71], 0, v[146:147]
	global_load_dwordx4 v[164:167], v[142:143], off
	s_nop 0
	global_load_dwordx4 v[168:171], v[168:169], off
	s_nop 0
	global_load_dwordx4 v[172:175], v[172:173], off
	s_nop 0
	global_load_dwordx4 v[176:179], v[176:177], off
	s_nop 0
	global_load_dwordx4 v[180:183], v[180:181], off
	v_mov_b32_e32 v61, v147
	v_mov_b32_e32 v63, v147
	v_ashrrev_i32_e32 v41, 31, v40
	s_waitcnt vmcnt(27)
	v_pk_add_f32 v[2:3], v[2:3], v[10:11]
	v_pk_add_f32 v[0:1], v[0:1], v[8:9]
	v_lshl_add_u64 v[8:9], v[72:73], 0, v[146:147]
	global_load_dwordx4 v[184:187], v[8:9], off
	v_lshl_add_u64 v[8:9], v[74:75], 0, v[146:147]
	global_load_dwordx4 v[188:191], v[8:9], off
	s_waitcnt vmcnt(27)
	v_pk_add_f32 v[2:3], v[2:3], v[18:19]
	v_lshl_add_u64 v[8:9], v[76:77], 0, v[146:147]
	global_load_dwordx4 v[192:195], v[8:9], off
	v_pk_add_f32 v[0:1], v[0:1], v[16:17]
	v_pk_add_f32 v[4:5], v[4:5], v[12:13]
	s_waitcnt vmcnt(26)
	v_pk_add_f32 v[2:3], v[2:3], v[26:27]
	v_pk_add_f32 v[0:1], v[0:1], v[24:25]
	v_pk_add_f32 v[6:7], v[6:7], v[14:15]
	s_waitcnt vmcnt(24)
	v_pk_add_f32 v[2:3], v[2:3], v[34:35]
	v_pk_add_f32 v[0:1], v[0:1], v[32:33]
	s_waitcnt vmcnt(23)
	v_pk_add_f32 v[8:9], v[2:3], v[88:89]
	v_lshl_add_u64 v[2:3], v[78:79], 0, v[146:147]
	global_load_dwordx4 v[196:199], v[2:3], off
	v_lshl_add_u64 v[2:3], v[80:81], 0, v[146:147]
	global_load_dwordx4 v[210:213], v[2:3], off
	v_pk_add_f32 v[10:11], v[0:1], v[86:87]
	v_lshl_add_u64 v[0:1], v[82:83], 0, v[146:147]
	global_load_dwordx4 v[0:3], v[0:1], off
	v_pk_add_f32 v[4:5], v[4:5], v[20:21]
	v_pk_add_f32 v[6:7], v[6:7], v[22:23]
	v_pk_add_f32 v[4:5], v[4:5], v[28:29]
	v_pk_add_f32 v[6:7], v[6:7], v[30:31]
	s_waitcnt vmcnt(24)
	v_pk_add_f32 v[4:5], v[4:5], v[36:37]
	v_pk_add_f32 v[6:7], v[6:7], v[38:39]
	v_pk_add_f32 v[4:5], v[4:5], v[90:91]
	v_pk_add_f32 v[6:7], v[6:7], v[92:93]
	s_waitcnt vmcnt(22)
	v_pk_add_f32 v[4:5], v[4:5], v[110:111]
	v_pk_add_f32 v[6:7], v[6:7], v[112:113]
	s_waitcnt vmcnt(20)
	v_pk_add_f32 v[4:5], v[4:5], v[118:119]
	v_pk_add_f32 v[6:7], v[6:7], v[120:121]
	s_waitcnt vmcnt(18)
	v_pk_add_f32 v[4:5], v[4:5], v[126:127]
	v_pk_add_f32 v[8:9], v[8:9], v[108:109]
	v_pk_add_f32 v[10:11], v[10:11], v[106:107]
	v_pk_add_f32 v[6:7], v[6:7], v[128:129]
	v_pk_add_f32 v[4:5], v[4:5], 1.0 op_sel_hi:[1,0]
	v_pk_add_f32 v[8:9], v[8:9], v[116:117]
	v_pk_add_f32 v[10:11], v[10:11], v[114:115]
	v_pk_add_f32 v[6:7], v[6:7], 1.0 op_sel_hi:[1,0]
	s_waitcnt vmcnt(17)
	v_pk_mul_f32 v[92:93], v[130:131], v[4:5]
	v_lshl_add_u64 v[4:5], v[84:85], 0, v[146:147]
	v_pk_add_f32 v[86:87], v[8:9], v[124:125]
	v_pk_add_f32 v[88:89], v[10:11], v[122:123]
	global_load_dwordx4 v[8:11], v[50:51], off offset:1024
	v_pk_mul_f32 v[90:91], v[132:133], v[6:7]
	global_load_dwordx4 v[24:27], v[4:5], off
	s_nop 0
	global_load_dwordx4 v[4:7], v[54:55], off
	s_waitcnt vmcnt(16)
	v_pk_add_f32 v[16:17], v[150:151], v[154:155]
	v_pk_add_f32 v[12:13], v[136:137], v[140:141]
	v_pk_add_f32 v[14:15], v[134:135], v[138:139]
	s_waitcnt vmcnt(14)
	v_pk_add_f32 v[128:129], v[16:17], v[162:163]
	v_lshl_add_u64 v[16:17], v[94:95], 0, v[60:61]
	v_lshl_add_u64 v[20:21], v[96:97], 0, v[60:61]
	v_pk_add_f32 v[124:125], v[12:13], v[158:159]
	v_pk_add_f32 v[126:127], v[14:15], v[156:157]
	global_load_dwordx4 v[12:15], v[46:47], off offset:2048
	v_lshl_add_u64 v[28:29], v[98:99], 0, v[60:61]
	global_load_dwordx4 v[16:19], v[16:17], off
	v_lshl_add_u64 v[32:33], v[100:101], 0, v[60:61]
	global_load_dwordx4 v[20:23], v[20:21], off
	v_lshl_add_u64 v[36:37], v[102:103], 0, v[60:61]
	global_load_dwordx4 v[28:31], v[28:29], off
	v_lshl_add_u64 v[106:107], v[64:65], 0, v[60:61]
	global_load_dwordx4 v[32:35], v[32:33], off
	v_lshl_add_u64 v[110:111], v[66:67], 0, v[60:61]
	global_load_dwordx4 v[36:39], v[36:37], off
	v_lshl_add_u64 v[114:115], v[68:69], 0, v[60:61]
	global_load_dwordx4 v[106:109], v[106:107], off
	v_pk_add_f32 v[122:123], v[148:149], v[152:153]
	global_load_dwordx4 v[110:113], v[110:111], off
	v_lshl_add_u64 v[118:119], v[70:71], 0, v[60:61]
	global_load_dwordx4 v[114:117], v[114:115], off
	v_pk_add_f32 v[130:131], v[122:123], v[160:161]
	global_load_dwordx4 v[118:121], v[118:119], off
	v_lshl_add_u64 v[122:123], v[72:73], 0, v[60:61]
	s_waitcnt vmcnt(23)
	v_pk_add_f32 v[132:133], v[124:125], v[166:167]
	global_load_dwordx4 v[122:125], v[122:123], off
	v_pk_add_f32 v[126:127], v[126:127], v[164:165]
	s_waitcnt vmcnt(23)
	v_pk_add_f32 v[128:129], v[128:129], v[170:171]
	s_waitcnt vmcnt(22)
	v_pk_add_f32 v[134:135], v[126:127], v[172:173]
	v_lshl_add_u64 v[126:127], v[74:75], 0, v[60:61]
	s_waitcnt vmcnt(21)
	v_pk_add_f32 v[136:137], v[128:129], v[178:179]
	global_load_dwordx4 v[126:129], v[126:127], off
	v_pk_add_f32 v[130:131], v[130:131], v[168:169]
	v_pk_add_f32 v[132:133], v[132:133], v[174:175]
	v_pk_add_f32 v[138:139], v[130:131], v[176:177]
	s_waitcnt vmcnt(21)
	v_pk_add_f32 v[134:135], v[134:135], v[180:181]
	v_lshl_add_u64 v[130:131], v[76:77], 0, v[60:61]
	v_pk_add_f32 v[140:141], v[132:133], v[182:183]
	s_waitcnt vmcnt(20)
	v_pk_add_f32 v[136:137], v[136:137], v[186:187]
	global_load_dwordx4 v[130:133], v[130:131], off
	v_pk_add_f32 v[138:139], v[138:139], v[184:185]
	s_waitcnt vmcnt(20)
	v_pk_add_f32 v[142:143], v[134:135], v[188:189]
	v_lshl_add_u64 v[134:135], v[78:79], 0, v[60:61]
	v_pk_add_f32 v[140:141], v[140:141], v[190:191]
	s_waitcnt vmcnt(19)
	v_pk_add_f32 v[148:149], v[136:137], v[194:195]
	global_load_dwordx4 v[134:137], v[134:135], off
	v_pk_add_f32 v[150:151], v[138:139], v[192:193]
	v_lshl_add_u64 v[138:139], v[80:81], 0, v[60:61]
	s_waitcnt vmcnt(19)
	v_pk_add_f32 v[152:153], v[140:141], v[198:199]
	s_waitcnt vmcnt(18)
	v_pk_add_f32 v[184:185], v[148:149], v[212:213]
	global_load_dwordx4 v[138:141], v[138:139], off
	v_lshl_add_u64 v[148:149], v[82:83], 0, v[60:61]
	v_pk_add_f32 v[186:187], v[150:151], v[210:211]
	global_load_dwordx4 v[148:151], v[148:149], off
	s_waitcnt vmcnt(19)
	v_pk_add_f32 v[2:3], v[152:153], v[2:3]
	v_lshl_add_u64 v[152:153], v[84:85], 0, v[60:61]
	global_load_dwordx4 v[152:155], v[152:153], off
	s_nop 0
	global_load_dwordx4 v[156:159], v[50:51], off offset:2048
	global_load_dwordx4 v[160:163], v[46:47], off offset:3072
	global_load_dwordx4 v[164:167], v[56:57], off
	v_lshl_add_u64 v[94:95], v[94:95], 0, v[62:63]
	v_lshl_add_u64 v[168:169], v[96:97], 0, v[62:63]
	v_lshl_add_u64 v[98:99], v[98:99], 0, v[62:63]
	v_lshl_add_u64 v[172:173], v[100:101], 0, v[62:63]
	v_lshl_add_u64 v[102:103], v[102:103], 0, v[62:63]
	global_load_dwordx4 v[94:97], v[94:95], off
	s_nop 0
	global_load_dwordx4 v[168:171], v[168:169], off
	s_nop 0
	global_load_dwordx4 v[98:101], v[98:99], off
	s_nop 0
	global_load_dwordx4 v[172:175], v[172:173], off
	v_pk_add_f32 v[142:143], v[142:143], v[196:197]
	global_load_dwordx4 v[176:179], v[102:103], off
	v_lshlrev_b64 v[102:103], 12, v[40:41]
	v_lshl_add_u64 v[102:103], v[58:59], 0, v[102:103]
	global_load_dwordx4 v[180:183], v[102:103], off
	v_pk_add_f32 v[0:1], v[142:143], v[0:1]
	s_waitcnt vmcnt(27)
	v_pk_add_f32 v[26:27], v[184:185], v[26:27]
	v_pk_add_f32 v[142:143], v[186:187], v[24:25]
	v_pk_add_f32 v[184:185], v[26:27], 1.0 op_sel_hi:[1,0]
	global_load_dwordx4 v[24:27], v[102:103], off offset:1024
	v_pk_add_f32 v[142:143], v[142:143], 1.0 op_sel_hi:[1,0]
	v_pk_mul_f32 v[188:189], v[10:11], v[184:185]
	v_pk_mul_f32 v[142:143], v[8:9], v[142:143]
	global_load_dwordx4 v[8:11], v[102:103], off offset:2048
	global_load_dwordx4 v[184:187], v[102:103], off offset:3072
	s_waitcnt vmcnt(27)
	v_pk_add_f32 v[12:13], v[12:13], v[16:17]
	v_pk_add_f32 v[14:15], v[14:15], v[18:19]
	s_waitcnt vmcnt(26)
	v_pk_add_f32 v[4:5], v[4:5], v[20:21]
	v_pk_add_f32 v[6:7], v[6:7], v[22:23]
	s_waitcnt vmcnt(25)
	v_pk_add_f32 v[12:13], v[12:13], v[28:29]
	v_pk_add_f32 v[14:15], v[14:15], v[30:31]
	s_waitcnt vmcnt(24)
	v_pk_add_f32 v[4:5], v[4:5], v[32:33]
	v_pk_add_f32 v[6:7], v[6:7], v[34:35]
	s_waitcnt vmcnt(23)
	v_pk_add_f32 v[12:13], v[12:13], v[36:37]
	v_pk_add_f32 v[14:15], v[14:15], v[38:39]
	s_waitcnt vmcnt(22)
	v_pk_add_f32 v[4:5], v[4:5], v[106:107]
	v_pk_add_f32 v[6:7], v[6:7], v[108:109]
	s_waitcnt vmcnt(21)
	v_pk_add_f32 v[16:17], v[12:13], v[110:111]
	v_pk_add_f32 v[14:15], v[14:15], v[112:113]
	s_waitcnt vmcnt(20)
	v_pk_add_f32 v[28:29], v[4:5], v[114:115]
	v_lshl_add_u64 v[4:5], v[64:65], 0, v[62:63]
	v_pk_add_f32 v[18:19], v[6:7], v[116:117]
	global_load_dwordx4 v[4:7], v[4:5], off
	s_waitcnt vmcnt(20)
	v_pk_add_f32 v[36:37], v[16:17], v[118:119]
	v_lshl_add_u64 v[16:17], v[68:69], 0, v[62:63]
	s_waitcnt vmcnt(19)
	v_pk_add_f32 v[38:39], v[18:19], v[124:125]
	global_load_dwordx4 v[16:19], v[16:17], off
	v_lshl_add_u64 v[12:13], v[66:67], 0, v[62:63]
	v_pk_add_f32 v[30:31], v[14:15], v[120:121]
	global_load_dwordx4 v[12:15], v[12:13], off
	v_lshl_add_u64 v[20:21], v[70:71], 0, v[62:63]
	global_load_dwordx4 v[20:23], v[20:21], off
	v_pk_add_f32 v[68:69], v[28:29], v[122:123]
	v_lshl_add_u64 v[28:29], v[72:73], 0, v[62:63]
	s_waitcnt vmcnt(21)
	v_pk_add_f32 v[70:71], v[30:31], v[128:129]
	global_load_dwordx4 v[28:31], v[28:29], off
	v_pk_add_f32 v[102:103], v[36:37], v[126:127]
	v_lshl_add_u64 v[36:37], v[76:77], 0, v[62:63]
	s_waitcnt vmcnt(21)
	v_pk_add_f32 v[106:107], v[38:39], v[132:133]
	global_load_dwordx4 v[36:39], v[36:37], off
	v_lshl_add_u64 v[64:65], v[78:79], 0, v[62:63]
	v_pk_add_f32 v[108:109], v[68:69], v[130:131]
	v_lshl_add_u64 v[68:69], v[80:81], 0, v[62:63]
	v_lshl_add_u64 v[32:33], v[74:75], 0, v[62:63]
	global_load_dwordx4 v[64:67], v[64:65], off
	s_waitcnt vmcnt(22)
	v_pk_add_f32 v[110:111], v[70:71], v[136:137]
	global_load_dwordx4 v[68:71], v[68:69], off
	v_lshl_add_u64 v[72:73], v[82:83], 0, v[62:63]
	v_lshl_add_u64 v[76:77], v[84:85], 0, v[62:63]
	global_load_dwordx4 v[32:35], v[32:33], off
	v_pk_add_f32 v[80:81], v[102:103], v[134:135]
	global_load_dwordx4 v[72:75], v[72:73], off
	s_waitcnt vmcnt(24)
	v_pk_add_f32 v[82:83], v[106:107], v[140:141]
	global_load_dwordx4 v[76:79], v[76:77], off
	v_pk_add_f32 v[84:85], v[108:109], v[138:139]
	s_waitcnt vmcnt(24)
	v_pk_add_f32 v[106:107], v[80:81], v[148:149]
	s_waitcnt vmcnt(23)
	v_pk_add_f32 v[80:81], v[82:83], v[154:155]
	v_pk_add_f32 v[82:83], v[84:85], v[152:153]
	v_pk_add_f32 v[84:85], v[80:81], 1.0 op_sel_hi:[1,0]
	v_pk_add_f32 v[108:109], v[82:83], 1.0 op_sel_hi:[1,0]
	global_load_dwordx4 v[80:83], v[50:51], off offset:3072
	v_pk_add_f32 v[102:103], v[110:111], v[150:151]
	s_waitcnt vmcnt(20)
	v_pk_add_f32 v[96:97], v[162:163], v[96:97]
	v_pk_add_f32 v[94:95], v[160:161], v[94:95]
	s_waitcnt vmcnt(19)
	v_pk_add_f32 v[110:111], v[166:167], v[170:171]
	v_pk_add_f32 v[112:113], v[164:165], v[168:169]
	s_waitcnt vmcnt(18)
	v_pk_add_f32 v[96:97], v[96:97], v[100:101]
	v_pk_add_f32 v[94:95], v[94:95], v[98:99]
	s_waitcnt vmcnt(17)
	v_pk_add_f32 v[98:99], v[110:111], v[174:175]
	v_pk_add_f32 v[100:101], v[112:113], v[172:173]
	s_waitcnt vmcnt(15)
	v_pk_mul_f32 v[110:111], v[182:183], v[182:183]
	v_pk_mul_f32 v[112:113], v[180:181], v[180:181]
	v_pk_add_f32 v[96:97], v[96:97], v[178:179]
	v_pk_mov_b32 v[114:115], v[112:113], v[110:111] op_sel:[1,0]
	v_mov_b32_e32 v113, v111
	v_pk_add_f32 v[110:111], v[114:115], v[112:113]
	s_waitcnt vmcnt(14)
	v_pk_mul_f32 v[112:113], v[26:27], v[26:27]
	v_pk_mul_f32 v[114:115], v[24:25], v[24:25]
	v_pk_add_f32 v[110:111], v[110:111], v[110:111] op_sel:[0,1] op_sel_hi:[1,0]
	v_pk_mov_b32 v[116:117], v[114:115], v[112:113] op_sel:[1,0]
	v_mov_b32_e32 v115, v113
	v_pk_add_f32 v[112:113], v[116:117], v[114:115]
	s_waitcnt vmcnt(12)
	v_mul_f32_e32 v61, v184, v184
	v_mul_f32_e32 v63, v185, v185
	v_pk_add_f32 v[112:113], v[112:113], v[112:113] op_sel:[0,1] op_sel_hi:[1,0]
	v_mov_b32_e32 v111, v61
	v_mov_b32_e32 v113, v63
	v_pk_add_f32 v[110:111], v[110:111], v[112:113]
	v_mul_f32_e32 v112, v9, v9
	v_mul_f32_e32 v114, v11, v11
	v_mul_f32_e32 v105, v186, v186
	v_mul_f32_e32 v116, v187, v187
	v_pk_fma_f32 v[112:113], v[8:9], v[8:9], v[112:113] op_sel_hi:[1,1,0]
	v_pk_fma_f32 v[114:115], v[10:11], v[10:11], v[114:115] op_sel_hi:[1,1,0]
	v_mov_b32_e32 v113, v105
	v_mov_b32_e32 v115, v116
	v_pk_add_f32 v[112:113], v[112:113], v[114:115]
	v_pk_add_f32 v[94:95], v[94:95], v[176:177]
	v_pk_add_f32 v[110:111], v[110:111], v[112:113]
	v_pk_mul_f32 v[108:109], v[156:157], v[108:109]
	v_add_f32_e32 v61, v110, v111
	s_nop 1
	v_mov_b32_dpp v63, v61 quad_perm:[1,0,3,2] row_mask:0xf bank_mask:0xf
	s_waitcnt vmcnt(11)
	v_pk_add_f32 v[4:5], v[100:101], v[4:5]
	v_pk_add_f32 v[6:7], v[98:99], v[6:7]
	v_pk_mul_f32 v[84:85], v[158:159], v[84:85]
	s_waitcnt lgkmcnt(0)
	v_add_f32_e32 v61, v61, v63
	s_nop 1
	v_mov_b32_dpp v63, v61 quad_perm:[2,3,0,1] row_mask:0xf bank_mask:0xf
	s_waitcnt vmcnt(10)
	v_pk_add_f32 v[4:5], v[4:5], v[16:17]
	v_pk_add_f32 v[6:7], v[6:7], v[18:19]
	s_waitcnt vmcnt(9)
	v_pk_add_f32 v[14:15], v[96:97], v[14:15]
	v_pk_add_f32 v[12:13], v[94:95], v[12:13]
	s_waitcnt lgkmcnt(0)
	v_add_f32_e32 v16, v61, v63
	s_nop 1
	v_mov_b32_dpp v17, v16 row_half_mirror row_mask:0xf bank_mask:0xf
	s_waitcnt vmcnt(8)
	v_pk_add_f32 v[14:15], v[14:15], v[22:23]
	v_pk_add_f32 v[12:13], v[12:13], v[20:21]
	s_waitcnt vmcnt(7)
	v_pk_add_f32 v[4:5], v[4:5], v[28:29]
	v_pk_add_f32 v[6:7], v[6:7], v[30:31]
	s_waitcnt lgkmcnt(0)
	v_add_f32_e32 v16, v16, v17
	s_nop 1
	v_mov_b32_dpp v17, v16 row_mirror row_mask:0xf bank_mask:0xf
	s_waitcnt vmcnt(6)
	v_pk_add_f32 v[4:5], v[4:5], v[36:37]
	v_pk_add_f32 v[6:7], v[6:7], v[38:39]
	s_waitcnt lgkmcnt(0)
	v_add_f32_e32 v16, v16, v17
	v_mov_b32_e32 v17, v16
	s_nop 1
	v_permlane16_swap_b32_e32 v17, v16
	s_nop 0
	s_waitcnt vmcnt(4)
	v_pk_add_f32 v[4:5], v[4:5], v[68:69]
	v_pk_add_f32 v[6:7], v[6:7], v[70:71]
	s_waitcnt vmcnt(3)
	v_pk_add_f32 v[12:13], v[12:13], v[32:33]
	s_waitcnt lgkmcnt(0)
	v_add_f32_e32 v16, v16, v17
	v_mov_b32_e32 v17, v16
	s_nop 1
	v_permlane32_swap_b32_e32 v17, v16
	s_nop 0
	v_pk_add_f32 v[14:15], v[14:15], v[34:35]
	s_waitcnt vmcnt(1)
	v_pk_add_f32 v[4:5], v[4:5], v[76:77]
	v_pk_add_f32 v[12:13], v[12:13], v[64:65]
	v_pk_add_f32 v[6:7], v[6:7], v[78:79]
	s_waitcnt lgkmcnt(0)
	v_add_f32_e32 v16, v16, v17
	v_fmamk_f32 v16, v16, 0x3a800000, v104
	v_mul_f32_e32 v17, 0x4b800000, v16
	v_cmp_gt_f32_e32 vcc, s48, v16
	v_pk_add_f32 v[4:5], v[4:5], 1.0 op_sel_hi:[1,0]
	v_pk_add_f32 v[14:15], v[14:15], v[66:67]
	v_cndmask_b32_e32 v16, v16, v17, vcc
	v_rsq_f32_e32 v18, v16
	v_lshlrev_b64 v[16:17], 11, v[40:41]
	v_lshl_add_u64 v[16:17], v[42:43], 0, v[16:17]
	v_lshl_add_u64 v[20:21], v[16:17], 0, s[46:47]
	v_mul_f32_e32 v19, 0x45800000, v18
	v_cndmask_b32_e32 v18, v18, v19, vcc
	v_pk_mul_f32 v[22:23], v[180:181], v[18:19] op_sel_hi:[1,0]
	v_add_co_u32_e32 v16, vcc, s49, v16
	v_pk_mul_f32 v[28:29], v[182:183], v[18:19] op_sel_hi:[1,0]
	v_pk_fma_f32 v[22:23], v[92:93], v[22:23], v[88:89]
	v_addc_co_u32_e32 v17, vcc, 0, v17, vcc
	v_pk_fma_f32 v[28:29], v[90:91], v[28:29], v[86:87]
	v_cvt_pk_bf16_f32 v22, v22, v23
	v_pk_add_f32 v[12:13], v[12:13], v[72:73]
	v_cvt_pk_bf16_f32 v23, v28, v29
	global_store_dwordx2 v[16:17], v[22:23], off
	v_pk_mul_f32 v[16:17], v[24:25], v[18:19] op_sel_hi:[1,0]
	v_pk_mul_f32 v[22:23], v[26:27], v[18:19] op_sel_hi:[1,0]
	v_pk_fma_f32 v[0:1], v[142:143], v[16:17], v[0:1]
	v_pk_fma_f32 v[2:3], v[188:189], v[22:23], v[2:3]
	v_cvt_pk_bf16_f32 v0, v0, v1
	v_pk_add_f32 v[6:7], v[6:7], 1.0 op_sel_hi:[1,0]
	v_cvt_pk_bf16_f32 v1, v2, v3
	global_store_dwordx2 v[20:21], v[0:1], off offset:512
	v_pk_mul_f32 v[0:1], v[8:9], v[18:19] op_sel_hi:[1,0]
	v_pk_mul_f32 v[2:3], v[10:11], v[18:19] op_sel_hi:[1,0]
	v_pk_fma_f32 v[0:1], v[108:109], v[0:1], v[106:107]
	v_pk_fma_f32 v[2:3], v[84:85], v[2:3], v[102:103]
	v_cvt_pk_bf16_f32 v0, v0, v1
	s_waitcnt vmcnt(2)
	v_pk_mul_f32 v[4:5], v[80:81], v[4:5]
	v_cvt_pk_bf16_f32 v1, v2, v3
	global_store_dwordx2 v[20:21], v[0:1], off offset:1024
	v_pk_mul_f32 v[0:1], v[184:185], v[18:19] op_sel_hi:[1,0]
	v_pk_add_f32 v[14:15], v[14:15], v[74:75]
	v_pk_mul_f32 v[6:7], v[82:83], v[6:7]
	v_pk_mul_f32 v[2:3], v[186:187], v[18:19] op_sel_hi:[1,0]
	v_pk_fma_f32 v[0:1], v[4:5], v[0:1], v[12:13]
	v_pk_fma_f32 v[2:3], v[6:7], v[2:3], v[14:15]
	v_cvt_pk_bf16_f32 v0, v0, v1
	s_nop 0
	v_cvt_pk_bf16_f32 v1, v2, v3
	global_store_dwordx2 v[20:21], v[0:1], off offset:1536
	s_load_dword s51, s[4:5], 0x0
	s_waitcnt lgkmcnt(0)
	v_lshl_add_u32 v40, s51, 3, v40
	v_cmp_lt_i32_e32 vcc, s50, v40
	s_or_b64 s[6:7], vcc, s[6:7]
	s_andn2_b64 exec, exec, s[6:7]
	s_cbranch_execnz .LBB0_156
